# scan S3: value fragments kept in registers from S2 (no re-read), P1 value products issued first so the A1 chain starts earlier
# baseline (speedup 1.0000x reference)
; #define LAS __attribute__((address_space(3)))
; #define MFMA32(a, b, c) __builtin_amdgcn_mfma_f32_32x32x16_bf16((a), (b), (c), 0, 0, 0)
; __device__ __forceinline__ void scan_pass1(const ScanP& sp, int b, int h, int seg, LAS unsigned char* lds) {
;     ...
;         if (w < 4) {
; #pragma unroll
;             for (int i = 0; i < 16; ++i) { P1[i] = 0.f; P2[i] = 0.f; }
; #pragma unroll
;             for (int jb = 0; jb < 2; ++jb)
; #pragma unroll
;                 for (int s = 0; s < 2; ++s) {
;                     const bf16x8 hb = pack8(Hacc[jb], s);
;                     const int off = (ln * 72 + 32 * jb + 16 * s + 4 * hh) * 2;
;                     P1 = MFMA32(ld_krow(lds + O_KK + off), hb, P1);
;                     P2 = MFMA32(ld_krow(lds + O_R + off), hb, P2);
;                 }
;     ...
;             for (int jb = 0; jb < 2; ++jb) {
;                 if (isH) {
; #pragma unroll
;                     for (int ks = 0; ks < 2; ++ks) Hacc[jb] = MFMA32(*(const LAS bf16x8*)(lds + O_KT + ((32 * jb + ln) * 40 + ks * 16 + hh * 8) * 2), vfr[ks], Hacc[jb]);
;                 }
.LBB0_284:
	s_andn2_b64 vcc, exec, s[0:1]
	s_cbranch_vccnz .LBB0_286
	v_lshlrev_b32_e32 v2, 3, v188
	v_add3_u32 v0, v2, v0, 0
	v_add_u32_e32 v2, 0x8000, v0
	v_add_u32_e32 v0, 0x9000, v0
	ds_read2_b64 v[36:39], v2 offset1:2
	ds_read2_b64 v[68:71], v2 offset0:4 offset1:6
	ds_read2_b64 v[56:59], v0 offset0:64 offset1:66
	ds_read2_b64 v[230:233], v0 offset0:68 offset1:70
	ds_read2_b64 v[234:237], v2 offset0:8 offset1:10
	ds_read2_b64 v[238:241], v0 offset0:72 offset1:74
	ds_read2_b64 v[242:245], v2 offset0:12 offset1:14
	ds_read2_b64 v[246:249], v0 offset0:76 offset1:78
	v_cvt_pk_bf16_f32 v52, v20, v21
	v_cvt_pk_bf16_f32 v53, v22, v23
	v_cvt_pk_bf16_f32 v54, v24, v25
	v_cvt_pk_bf16_f32 v55, v26, v27
	v_cvt_pk_bf16_f32 v72, v28, v29
	v_cvt_pk_bf16_f32 v73, v30, v31
	v_cvt_pk_bf16_f32 v74, v32, v33
	v_cvt_pk_bf16_f32 v75, v34, v35
	s_waitcnt lgkmcnt(7)
	s_nop 0
	v_mfma_f32_32x32x16_bf16 v[36:51], v[36:39], v[52:55], 0
	s_waitcnt lgkmcnt(6)
	v_mfma_f32_32x32x16_bf16 v[36:51], v[68:71], v[72:75], v[36:51]
	s_waitcnt lgkmcnt(5)
	v_mfma_f32_32x32x16_bf16 v[52:67], v[56:59], v[52:55], 0
	s_waitcnt lgkmcnt(4)
	v_mfma_f32_32x32x16_bf16 v[52:67], v[230:233], v[72:75], v[52:67]
	s_nop 1
	v_cvt_pk_bf16_f32 v72, v4, v5
	v_cvt_pk_bf16_f32 v73, v6, v7
	v_cvt_pk_bf16_f32 v74, v8, v9
	v_cvt_pk_bf16_f32 v75, v10, v11
	s_waitcnt lgkmcnt(3)
	s_nop 1
	v_mfma_f32_32x32x16_bf16 v[36:51], v[234:237], v[72:75], v[36:51]
	s_waitcnt lgkmcnt(2)
	v_mfma_f32_32x32x16_bf16 v[52:67], v[238:241], v[72:75], v[52:67]
	s_nop 1
	v_cvt_pk_bf16_f32 v72, v12, v13
	v_cvt_pk_bf16_f32 v73, v14, v15
	v_cvt_pk_bf16_f32 v74, v16, v17
	v_cvt_pk_bf16_f32 v75, v18, v19
	s_waitcnt lgkmcnt(1)
	s_nop 1
	v_mfma_f32_32x32x16_bf16 v[36:51], v[242:245], v[72:75], v[36:51]
	s_waitcnt lgkmcnt(0)
	v_mfma_f32_32x32x16_bf16 v[52:67], v[246:249], v[72:75], v[52:67]
	s_andn2_b64 vcc, exec, s[54:55]
	s_cbranch_vccnz .Lkt_skip
	v_or_b32_e32 v230, s82, v189
	v_mul_u32_u24_e32 v231, 0x50, v189
	v_lshlrev_b32_e32 v232, 4, v188
	v_mul_u32_u24_e32 v230, 0x50, v230
	v_add_u32_e32 v68, v231, v232
	v_add_u32_e32 v69, v230, v232
	ds_read_b128 v[92:95], v69 offset:61440
	ds_read_b128 v[238:241], v68 offset:51200
	ds_read_b128 v[246:249], v68 offset:53760
	ds_read_b128 v[96:99], v69 offset:61472
	ds_read_b128 v[242:245], v68 offset:51232
	ds_read_b128 v[68:71], v68 offset:53792
	s_waitcnt lgkmcnt(4)
	v_mfma_f32_32x32x16_bf16 v[20:35], v[238:241], v[92:95], v[20:35]
	s_waitcnt lgkmcnt(3)
	v_mfma_f32_32x32x16_bf16 v[4:19], v[246:249], v[92:95], v[4:19]
	s_waitcnt lgkmcnt(1)
	v_mfma_f32_32x32x16_bf16 v[20:35], v[242:245], v[96:99], v[20:35]
	s_waitcnt lgkmcnt(0)
	v_mfma_f32_32x32x16_bf16 v[4:19], v[68:71], v[96:99], v[4:19]

; #define LAS __attribute__((address_space(3)))
; #define MFMA32(a, b, c) __builtin_amdgcn_mfma_f32_32x32x16_bf16((a), (b), (c), 0, 0, 0)
; __device__ __forceinline__ void scan_pass1(const ScanP& sp, int b, int h, int seg, LAS unsigned char* lds) {
;     ...
;             if (isH) {
; #pragma unroll
;                 for (int ks = 0; ks < 2; ++ks) vfr[ks] = *(const LAS bf16x8*)(lds + O_VT + (icol * 40 + ks * 16 + hh * 8) * 2);
; #pragma unroll
;                 for (int ks = 0; ks < 2; ++ks) {
;                     P1 = MFMA32(*(const LAS bf16x8*)(lds + O_MK + (ln * 40 + ks * 16 + hh * 8) * 2), vfr[ks], P1);
;                     P2 = MFMA32(*(const LAS bf16x8*)(lds + O_NK + (ln * 40 + ks * 16 + hh * 8) * 2), vfr[ks], P2);
;                 }
;             }
.LBB0_304:
	s_andn2_b64 vcc, exec, s[0:1]
	v_or_b32_e32 v121, s82, v189
	s_cbranch_vccnz .LBB0_309
	s_movk_i32 s0, 0x50
	v_mad_u32_u24 v72, v189, s0, v113
	s_add_i32 s0, 0, 0x10400
	s_add_i32 s1, 0, 0x10e00
	v_add_u32_e32 v230, s0, v72
	v_add_u32_e32 v231, s1, v72
	ds_read_b128 v[68:71], v230
	ds_read_b128 v[236:239], v230 offset:32
	ds_read_b128 v[232:235], v231
	ds_read_b128 v[240:243], v231 offset:32
	s_waitcnt lgkmcnt(3)
	v_mfma_f32_32x32x16_bf16 v[36:51], v[68:71], v[92:95], v[36:51]
	s_waitcnt lgkmcnt(2)
	v_mfma_f32_32x32x16_bf16 v[36:51], v[236:239], v[96:99], v[36:51]
	s_waitcnt lgkmcnt(1)
	v_mfma_f32_32x32x16_bf16 v[52:67], v[232:235], v[92:95], v[52:67]
	s_waitcnt lgkmcnt(0)
	v_mfma_f32_32x32x16_bf16 v[52:67], v[240:243], v[96:99], v[52:67]
	s_branch .LBB0_310
